# scan: output waves for chunk rows 0-31 skip the load and the two MFMAs of the second attn k-block, which is identically zero (attn is lower triangular); exact
# speedup vs baseline: 1.0106x; 1.0014x over previous
.Lscan_O_path:
	v_lshlrev_b32_e32 v2, 4, v14
	s_cmp_lt_u32 s12, 2
	s_cbranch_scc1 .Lscan_P_path
	global_load_dwordx4 v[72:75], v1, s[0:1]
	global_load_dwordx4 v[76:79], v1, s[0:1] offset:1024
	global_load_dwordx4 v[80:83], v1, s[0:1] offset:2048
	global_load_dwordx4 v[84:87], v1, s[0:1] offset:3072
	global_load_dwordx4 v[88:91], v2, s[2:3]
	global_load_dwordx4 v[92:95], v2, s[2:3] offset:1024
	global_load_dwordx4 v[96:99], v1, s[4:5]
	global_load_dwordx4 v[100:103], v1, s[4:5] offset:1024
	global_load_dword v184, v3, s[6:7]
	v_add_u32_e32 v1, 0x4000, v1
	v_add_u32_e32 v2, 0x2000, v2
	v_add_u32_e32 v3, 4, v3
	global_load_dwordx4 v[104:107], v1, s[0:1]
	global_load_dwordx4 v[108:111], v1, s[0:1] offset:1024
	global_load_dwordx4 v[112:115], v1, s[0:1] offset:2048
	global_load_dwordx4 v[116:119], v1, s[0:1] offset:3072
	global_load_dwordx4 v[120:123], v2, s[2:3]
	global_load_dwordx4 v[124:127], v2, s[2:3] offset:1024
	global_load_dwordx4 v[128:131], v1, s[4:5]
	global_load_dwordx4 v[132:135], v1, s[4:5] offset:1024
	global_load_dword v185, v3, s[6:7]
	v_add_u32_e32 v1, 0x4000, v1
	v_add_u32_e32 v2, 0x2000, v2
	v_add_u32_e32 v3, 4, v3
	global_load_dwordx4 v[136:139], v1, s[0:1]
	global_load_dwordx4 v[140:143], v1, s[0:1] offset:1024
	global_load_dwordx4 v[144:147], v1, s[0:1] offset:2048
	global_load_dwordx4 v[148:151], v1, s[0:1] offset:3072
	global_load_dwordx4 v[188:191], v2, s[2:3]
	global_load_dwordx4 v[192:195], v2, s[2:3] offset:1024
	global_load_dwordx4 v[196:199], v1, s[4:5]
	global_load_dwordx4 v[200:203], v1, s[4:5] offset:1024
	global_load_dword v186, v3, s[6:7]
	v_add_u32_e32 v1, 0x4000, v1
	v_add_u32_e32 v2, 0x2000, v2
	v_add_u32_e32 v3, 4, v3
	s_waitcnt vmcnt(0)
	s_movk_i32 s10, 32
.Lscan_O_loop:
	s_waitcnt vmcnt(26)
	ds_read_b128 v[32:35], v8 offset:0
	ds_read_b128 v[36:39], v8 offset:4352
	ds_read_b128 v[40:43], v8 offset:64
	ds_read_b128 v[44:47], v8 offset:4416
	ds_read_b128 v[48:51], v8 offset:128
	ds_read_b128 v[52:55], v8 offset:4480
	ds_read_b128 v[56:59], v8 offset:192
	ds_read_b128 v[60:63], v8 offset:4544
	global_load_dwordx4 v[216:219], v1, s[0:1]
	global_load_dwordx4 v[220:223], v1, s[0:1] offset:1024
	s_waitcnt vmcnt(23)
	v_mul_f32_e32 v16, v184, v16
	v_mul_f32_e32 v17, v184, v17
	v_mul_f32_e32 v18, v184, v18
	v_mul_f32_e32 v19, v184, v19
	global_load_dwordx4 v[224:227], v1, s[0:1] offset:2048
	v_mul_f32_e32 v20, v184, v20
	v_mul_f32_e32 v21, v184, v21
	v_mul_f32_e32 v22, v184, v22
	v_mul_f32_e32 v23, v184, v23
	global_load_dwordx4 v[228:231], v1, s[0:1] offset:3072
	s_waitcnt lgkmcnt(6)
	v_mfma_f32_16x16x32_bf16 v[24:27], v[72:75], v[32:35], 0
	v_mfma_f32_16x16x32_bf16 v[28:31], v[72:75], v[36:39], 0
	global_load_dwordx4 v[232:235], v2, s[2:3]
	s_waitcnt lgkmcnt(4)
	v_mfma_f32_16x16x32_bf16 v[24:27], v[76:79], v[40:43], v[24:27]
	v_mfma_f32_16x16x32_bf16 v[28:31], v[76:79], v[44:47], v[28:31]
	global_load_dwordx4 v[236:239], v2, s[2:3] offset:1024
	s_waitcnt lgkmcnt(2)
	v_mfma_f32_16x16x32_bf16 v[24:27], v[80:83], v[48:51], v[24:27]
	v_mfma_f32_16x16x32_bf16 v[28:31], v[80:83], v[52:55], v[28:31]
	global_load_dwordx4 v[240:243], v1, s[4:5]
	s_waitcnt lgkmcnt(0)
	v_mfma_f32_16x16x32_bf16 v[24:27], v[84:87], v[56:59], v[24:27]
	v_mfma_f32_16x16x32_bf16 v[28:31], v[84:87], v[60:63], v[28:31]
	global_load_dwordx4 v[244:247], v1, s[4:5] offset:1024
	global_load_dword v187, v3, s[6:7]
	v_add_u32_e32 v1, 0x4000, v1
	v_add_u32_e32 v2, 0x2000, v2
	v_add_u32_e32 v3, 4, v3
	s_waitcnt lgkmcnt(0)
	s_barrier
	ds_read_b128 v[32:35], v9 offset:17408
	ds_read_b128 v[36:39], v9 offset:19712
	ds_read_b128 v[40:43], v9 offset:17472
	ds_read_b128 v[44:47], v9 offset:19776
	s_waitcnt lgkmcnt(2)
	v_mfma_f32_16x16x32_bf16 v[16:19], v[96:99], v[32:35], v[16:19]
	v_mfma_f32_16x16x32_bf16 v[20:23], v[96:99], v[36:39], v[20:23]
	v_mfma_f32_16x16x32_bf16 v[24:27], v[88:91], v[32:35], v[24:27]
	v_mfma_f32_16x16x32_bf16 v[28:31], v[88:91], v[36:39], v[28:31]
	s_waitcnt lgkmcnt(0)
	v_mfma_f32_16x16x32_bf16 v[16:19], v[100:103], v[40:43], v[16:19]
	v_mfma_f32_16x16x32_bf16 v[20:23], v[100:103], v[44:47], v[20:23]
	v_mfma_f32_16x16x32_bf16 v[24:27], v[92:95], v[40:43], v[24:27]
	v_mfma_f32_16x16x32_bf16 v[28:31], v[92:95], v[44:47], v[28:31]
	s_nop 5
	v_cvt_pk_bf16_f32 v64, v16, v17
	v_cvt_pk_bf16_f32 v65, v18, v19
	v_cvt_pk_bf16_f32 v66, v20, v21
	v_cvt_pk_bf16_f32 v67, v22, v23
	ds_write_b64 v11, v[64:65] offset:8704
	ds_write_b64 v11, v[66:67] offset:13056
	v_cvt_pk_bf16_f32 v68, v24, v25
	v_cvt_pk_bf16_f32 v69, v26, v27
	v_cvt_pk_bf16_f32 v70, v28, v29
	v_cvt_pk_bf16_f32 v71, v30, v31
	ds_write_b16 v13, v68 offset:0
	ds_write_b16_d16_hi v13, v68 offset:80
	ds_write_b16 v13, v69 offset:160
	ds_write_b16_d16_hi v13, v69 offset:240
	ds_write_b16 v13, v70 offset:32
	ds_write_b16_d16_hi v13, v70 offset:112
	ds_write_b16 v13, v71 offset:192
	ds_write_b16_d16_hi v13, v71 offset:272
	ds_read_b128 v[176:179], v172
	s_waitcnt lgkmcnt(0)
	s_barrier
	global_store_dwordx4 v12, v[176:179], s[8:9]
	v_add_u32_e32 v12, 0x20000, v12
	s_waitcnt vmcnt(26)
	ds_read_b128 v[32:35], v8 offset:8704
	ds_read_b128 v[36:39], v8 offset:13056
	ds_read_b128 v[40:43], v8 offset:8768
	ds_read_b128 v[44:47], v8 offset:13120
	ds_read_b128 v[48:51], v8 offset:8832
	ds_read_b128 v[52:55], v8 offset:13184
	ds_read_b128 v[56:59], v8 offset:8896
	ds_read_b128 v[60:63], v8 offset:13248
	global_load_dwordx4 v[72:75], v1, s[0:1]
	global_load_dwordx4 v[76:79], v1, s[0:1] offset:1024
	s_waitcnt vmcnt(23)
	v_mul_f32_e32 v16, v185, v16
	v_mul_f32_e32 v17, v185, v17
	v_mul_f32_e32 v18, v185, v18
	v_mul_f32_e32 v19, v185, v19
	global_load_dwordx4 v[80:83], v1, s[0:1] offset:2048
	v_mul_f32_e32 v20, v185, v20
	v_mul_f32_e32 v21, v185, v21
	v_mul_f32_e32 v22, v185, v22
	v_mul_f32_e32 v23, v185, v23
	global_load_dwordx4 v[84:87], v1, s[0:1] offset:3072
	s_waitcnt lgkmcnt(6)
	v_mfma_f32_16x16x32_bf16 v[24:27], v[104:107], v[32:35], 0
	v_mfma_f32_16x16x32_bf16 v[28:31], v[104:107], v[36:39], 0
	global_load_dwordx4 v[88:91], v2, s[2:3]
	s_waitcnt lgkmcnt(4)
	v_mfma_f32_16x16x32_bf16 v[24:27], v[108:111], v[40:43], v[24:27]
	v_mfma_f32_16x16x32_bf16 v[28:31], v[108:111], v[44:47], v[28:31]
	global_load_dwordx4 v[92:95], v2, s[2:3] offset:1024
	s_waitcnt lgkmcnt(2)
	v_mfma_f32_16x16x32_bf16 v[24:27], v[112:115], v[48:51], v[24:27]
	v_mfma_f32_16x16x32_bf16 v[28:31], v[112:115], v[52:55], v[28:31]
	global_load_dwordx4 v[96:99], v1, s[4:5]
	s_waitcnt lgkmcnt(0)
	v_mfma_f32_16x16x32_bf16 v[24:27], v[116:119], v[56:59], v[24:27]
	v_mfma_f32_16x16x32_bf16 v[28:31], v[116:119], v[60:63], v[28:31]
	global_load_dwordx4 v[100:103], v1, s[4:5] offset:1024
	global_load_dword v184, v3, s[6:7]
	v_add_u32_e32 v1, 0x4000, v1
	v_add_u32_e32 v2, 0x2000, v2
	v_add_u32_e32 v3, 4, v3
	s_waitcnt lgkmcnt(0)
	s_barrier
	ds_read_b128 v[32:35], v9 offset:17408
	ds_read_b128 v[36:39], v9 offset:19712
	ds_read_b128 v[40:43], v9 offset:17472
	ds_read_b128 v[44:47], v9 offset:19776
	s_waitcnt lgkmcnt(2)
	v_mfma_f32_16x16x32_bf16 v[16:19], v[128:131], v[32:35], v[16:19]
	v_mfma_f32_16x16x32_bf16 v[20:23], v[128:131], v[36:39], v[20:23]
	v_mfma_f32_16x16x32_bf16 v[24:27], v[120:123], v[32:35], v[24:27]
	v_mfma_f32_16x16x32_bf16 v[28:31], v[120:123], v[36:39], v[28:31]
	s_waitcnt lgkmcnt(0)
	v_mfma_f32_16x16x32_bf16 v[16:19], v[132:135], v[40:43], v[16:19]
	v_mfma_f32_16x16x32_bf16 v[20:23], v[132:135], v[44:47], v[20:23]
	v_mfma_f32_16x16x32_bf16 v[24:27], v[124:127], v[40:43], v[24:27]
	v_mfma_f32_16x16x32_bf16 v[28:31], v[124:127], v[44:47], v[28:31]
	s_nop 5
	v_cvt_pk_bf16_f32 v64, v16, v17
	v_cvt_pk_bf16_f32 v65, v18, v19
	v_cvt_pk_bf16_f32 v66, v20, v21
	v_cvt_pk_bf16_f32 v67, v22, v23
	ds_write_b64 v11, v[64:65] offset:0
	ds_write_b64 v11, v[66:67] offset:4352
	v_cvt_pk_bf16_f32 v68, v24, v25
	v_cvt_pk_bf16_f32 v69, v26, v27
	v_cvt_pk_bf16_f32 v70, v28, v29
	v_cvt_pk_bf16_f32 v71, v30, v31
	ds_write_b16 v13, v68 offset:0
	ds_write_b16_d16_hi v13, v68 offset:80
	ds_write_b16 v13, v69 offset:160
	ds_write_b16_d16_hi v13, v69 offset:240
	ds_write_b16 v13, v70 offset:32
	ds_write_b16_d16_hi v13, v70 offset:112
	ds_write_b16 v13, v71 offset:192
	ds_write_b16_d16_hi v13, v71 offset:272
	ds_read_b128 v[176:179], v172
	s_waitcnt lgkmcnt(0)
	s_barrier
	global_store_dwordx4 v12, v[176:179], s[8:9]
	v_add_u32_e32 v12, 0x20000, v12
	s_waitcnt vmcnt(26)
	ds_read_b128 v[32:35], v8 offset:0
	ds_read_b128 v[36:39], v8 offset:4352
	ds_read_b128 v[40:43], v8 offset:64
	ds_read_b128 v[44:47], v8 offset:4416
	ds_read_b128 v[48:51], v8 offset:128
	ds_read_b128 v[52:55], v8 offset:4480
	ds_read_b128 v[56:59], v8 offset:192
	ds_read_b128 v[60:63], v8 offset:4544
	global_load_dwordx4 v[104:107], v1, s[0:1]
	global_load_dwordx4 v[108:111], v1, s[0:1] offset:1024
	s_waitcnt vmcnt(23)
	v_mul_f32_e32 v16, v186, v16
	v_mul_f32_e32 v17, v186, v17
	v_mul_f32_e32 v18, v186, v18
	v_mul_f32_e32 v19, v186, v19
	global_load_dwordx4 v[112:115], v1, s[0:1] offset:2048
	v_mul_f32_e32 v20, v186, v20
	v_mul_f32_e32 v21, v186, v21
	v_mul_f32_e32 v22, v186, v22
	v_mul_f32_e32 v23, v186, v23
	global_load_dwordx4 v[116:119], v1, s[0:1] offset:3072
	s_waitcnt lgkmcnt(6)
	v_mfma_f32_16x16x32_bf16 v[24:27], v[136:139], v[32:35], 0
	v_mfma_f32_16x16x32_bf16 v[28:31], v[136:139], v[36:39], 0
	global_load_dwordx4 v[120:123], v2, s[2:3]
	s_waitcnt lgkmcnt(4)
	v_mfma_f32_16x16x32_bf16 v[24:27], v[140:143], v[40:43], v[24:27]
	v_mfma_f32_16x16x32_bf16 v[28:31], v[140:143], v[44:47], v[28:31]
	global_load_dwordx4 v[124:127], v2, s[2:3] offset:1024
	s_waitcnt lgkmcnt(2)
	v_mfma_f32_16x16x32_bf16 v[24:27], v[144:147], v[48:51], v[24:27]
	v_mfma_f32_16x16x32_bf16 v[28:31], v[144:147], v[52:55], v[28:31]
	global_load_dwordx4 v[128:131], v1, s[4:5]
	s_waitcnt lgkmcnt(0)
	v_mfma_f32_16x16x32_bf16 v[24:27], v[148:151], v[56:59], v[24:27]
	v_mfma_f32_16x16x32_bf16 v[28:31], v[148:151], v[60:63], v[28:31]
	global_load_dwordx4 v[132:135], v1, s[4:5] offset:1024
	global_load_dword v185, v3, s[6:7]
	v_add_u32_e32 v1, 0x4000, v1
	v_add_u32_e32 v2, 0x2000, v2
	v_add_u32_e32 v3, 4, v3
	s_waitcnt lgkmcnt(0)
	s_barrier
	ds_read_b128 v[32:35], v9 offset:17408
	ds_read_b128 v[36:39], v9 offset:19712
	ds_read_b128 v[40:43], v9 offset:17472
	ds_read_b128 v[44:47], v9 offset:19776
	s_waitcnt lgkmcnt(2)
	v_mfma_f32_16x16x32_bf16 v[16:19], v[196:199], v[32:35], v[16:19]
	v_mfma_f32_16x16x32_bf16 v[20:23], v[196:199], v[36:39], v[20:23]
	v_mfma_f32_16x16x32_bf16 v[24:27], v[188:191], v[32:35], v[24:27]
	v_mfma_f32_16x16x32_bf16 v[28:31], v[188:191], v[36:39], v[28:31]
	s_waitcnt lgkmcnt(0)
	v_mfma_f32_16x16x32_bf16 v[16:19], v[200:203], v[40:43], v[16:19]
	v_mfma_f32_16x16x32_bf16 v[20:23], v[200:203], v[44:47], v[20:23]
	v_mfma_f32_16x16x32_bf16 v[24:27], v[192:195], v[40:43], v[24:27]
	v_mfma_f32_16x16x32_bf16 v[28:31], v[192:195], v[44:47], v[28:31]
	s_nop 5
	v_cvt_pk_bf16_f32 v64, v16, v17
	v_cvt_pk_bf16_f32 v65, v18, v19
	v_cvt_pk_bf16_f32 v66, v20, v21
	v_cvt_pk_bf16_f32 v67, v22, v23
	ds_write_b64 v11, v[64:65] offset:8704
	ds_write_b64 v11, v[66:67] offset:13056
	v_cvt_pk_bf16_f32 v68, v24, v25
	v_cvt_pk_bf16_f32 v69, v26, v27
	v_cvt_pk_bf16_f32 v70, v28, v29
	v_cvt_pk_bf16_f32 v71, v30, v31
	ds_write_b16 v13, v68 offset:0
	ds_write_b16_d16_hi v13, v68 offset:80
	ds_write_b16 v13, v69 offset:160
	ds_write_b16_d16_hi v13, v69 offset:240
	ds_write_b16 v13, v70 offset:32
	ds_write_b16_d16_hi v13, v70 offset:112
	ds_write_b16 v13, v71 offset:192
	ds_write_b16_d16_hi v13, v71 offset:272
	ds_read_b128 v[176:179], v172
	s_waitcnt lgkmcnt(0)
	s_barrier
	global_store_dwordx4 v12, v[176:179], s[8:9]
	v_add_u32_e32 v12, 0x20000, v12
	s_waitcnt vmcnt(26)
	ds_read_b128 v[32:35], v8 offset:8704
	ds_read_b128 v[36:39], v8 offset:13056
	ds_read_b128 v[40:43], v8 offset:8768
	ds_read_b128 v[44:47], v8 offset:13120
	ds_read_b128 v[48:51], v8 offset:8832
	ds_read_b128 v[52:55], v8 offset:13184
	ds_read_b128 v[56:59], v8 offset:8896
	ds_read_b128 v[60:63], v8 offset:13248
	global_load_dwordx4 v[136:139], v1, s[0:1]
	global_load_dwordx4 v[140:143], v1, s[0:1] offset:1024
	s_waitcnt vmcnt(23)
	v_mul_f32_e32 v16, v187, v16
	v_mul_f32_e32 v17, v187, v17
	v_mul_f32_e32 v18, v187, v18
	v_mul_f32_e32 v19, v187, v19
	global_load_dwordx4 v[144:147], v1, s[0:1] offset:2048
	v_mul_f32_e32 v20, v187, v20
	v_mul_f32_e32 v21, v187, v21
	v_mul_f32_e32 v22, v187, v22
	v_mul_f32_e32 v23, v187, v23
	global_load_dwordx4 v[148:151], v1, s[0:1] offset:3072
	s_waitcnt lgkmcnt(6)
	v_mfma_f32_16x16x32_bf16 v[24:27], v[216:219], v[32:35], 0
	v_mfma_f32_16x16x32_bf16 v[28:31], v[216:219], v[36:39], 0
	global_load_dwordx4 v[188:191], v2, s[2:3]
	s_waitcnt lgkmcnt(4)
	v_mfma_f32_16x16x32_bf16 v[24:27], v[220:223], v[40:43], v[24:27]
	v_mfma_f32_16x16x32_bf16 v[28:31], v[220:223], v[44:47], v[28:31]
	global_load_dwordx4 v[192:195], v2, s[2:3] offset:1024
	s_waitcnt lgkmcnt(2)
	v_mfma_f32_16x16x32_bf16 v[24:27], v[224:227], v[48:51], v[24:27]
	v_mfma_f32_16x16x32_bf16 v[28:31], v[224:227], v[52:55], v[28:31]
	global_load_dwordx4 v[196:199], v1, s[4:5]
	s_waitcnt lgkmcnt(0)
	v_mfma_f32_16x16x32_bf16 v[24:27], v[228:231], v[56:59], v[24:27]
	v_mfma_f32_16x16x32_bf16 v[28:31], v[228:231], v[60:63], v[28:31]
	global_load_dwordx4 v[200:203], v1, s[4:5] offset:1024
	global_load_dword v186, v3, s[6:7]
	v_add_u32_e32 v1, 0x4000, v1
	v_add_u32_e32 v2, 0x2000, v2
	v_add_u32_e32 v3, 4, v3
	s_waitcnt lgkmcnt(0)
	s_barrier
	ds_read_b128 v[32:35], v9 offset:17408
	ds_read_b128 v[36:39], v9 offset:19712
	ds_read_b128 v[40:43], v9 offset:17472
	ds_read_b128 v[44:47], v9 offset:19776
	s_waitcnt lgkmcnt(2)
	v_mfma_f32_16x16x32_bf16 v[16:19], v[240:243], v[32:35], v[16:19]
	v_mfma_f32_16x16x32_bf16 v[20:23], v[240:243], v[36:39], v[20:23]
	v_mfma_f32_16x16x32_bf16 v[24:27], v[232:235], v[32:35], v[24:27]
	v_mfma_f32_16x16x32_bf16 v[28:31], v[232:235], v[36:39], v[28:31]
	s_waitcnt lgkmcnt(0)
	v_mfma_f32_16x16x32_bf16 v[16:19], v[244:247], v[40:43], v[16:19]
	v_mfma_f32_16x16x32_bf16 v[20:23], v[244:247], v[44:47], v[20:23]
	v_mfma_f32_16x16x32_bf16 v[24:27], v[236:239], v[40:43], v[24:27]
	v_mfma_f32_16x16x32_bf16 v[28:31], v[236:239], v[44:47], v[28:31]
	s_nop 5
	v_cvt_pk_bf16_f32 v64, v16, v17
	v_cvt_pk_bf16_f32 v65, v18, v19
	v_cvt_pk_bf16_f32 v66, v20, v21
	v_cvt_pk_bf16_f32 v67, v22, v23
	ds_write_b64 v11, v[64:65] offset:0
	ds_write_b64 v11, v[66:67] offset:4352
	v_cvt_pk_bf16_f32 v68, v24, v25
	v_cvt_pk_bf16_f32 v69, v26, v27
	v_cvt_pk_bf16_f32 v70, v28, v29
	v_cvt_pk_bf16_f32 v71, v30, v31
	ds_write_b16 v13, v68 offset:0
	ds_write_b16_d16_hi v13, v68 offset:80
	ds_write_b16 v13, v69 offset:160
	ds_write_b16_d16_hi v13, v69 offset:240
	ds_write_b16 v13, v70 offset:32
	ds_write_b16_d16_hi v13, v70 offset:112
	ds_write_b16 v13, v71 offset:192
	ds_write_b16_d16_hi v13, v71 offset:272
	ds_read_b128 v[176:179], v172
	s_waitcnt lgkmcnt(0)
	s_barrier
	global_store_dwordx4 v12, v[176:179], s[8:9]
	v_add_u32_e32 v12, 0x20000, v12
	s_sub_u32 s10, s10, 1
	s_cmp_lg_u32 s10, 0
	s_cbranch_scc1 .Lscan_O_loop
	s_branch .Lscan_done
.Lscan_P_path:
	global_load_dwordx4 v[72:75], v1, s[0:1]
	global_load_dwordx4 v[76:79], v1, s[0:1] offset:1024
	global_load_dwordx4 v[80:83], v1, s[0:1] offset:2048
	global_load_dwordx4 v[84:87], v1, s[0:1] offset:3072
	global_load_dwordx4 v[88:91], v2, s[2:3]
	global_load_dwordx4 v[96:99], v1, s[4:5]
	global_load_dwordx4 v[100:103], v1, s[4:5] offset:1024
	global_load_dword v184, v3, s[6:7]
	v_add_u32_e32 v1, 0x4000, v1
	v_add_u32_e32 v2, 0x2000, v2
	v_add_u32_e32 v3, 4, v3
	global_load_dwordx4 v[104:107], v1, s[0:1]
	global_load_dwordx4 v[108:111], v1, s[0:1] offset:1024
	global_load_dwordx4 v[112:115], v1, s[0:1] offset:2048
	global_load_dwordx4 v[116:119], v1, s[0:1] offset:3072
	global_load_dwordx4 v[120:123], v2, s[2:3]
	global_load_dwordx4 v[128:131], v1, s[4:5]
	global_load_dwordx4 v[132:135], v1, s[4:5] offset:1024
	global_load_dword v185, v3, s[6:7]
	v_add_u32_e32 v1, 0x4000, v1
	v_add_u32_e32 v2, 0x2000, v2
	v_add_u32_e32 v3, 4, v3
	global_load_dwordx4 v[136:139], v1, s[0:1]
	global_load_dwordx4 v[140:143], v1, s[0:1] offset:1024
	global_load_dwordx4 v[144:147], v1, s[0:1] offset:2048
	global_load_dwordx4 v[148:151], v1, s[0:1] offset:3072
	global_load_dwordx4 v[188:191], v2, s[2:3]
	global_load_dwordx4 v[196:199], v1, s[4:5]
	global_load_dwordx4 v[200:203], v1, s[4:5] offset:1024
	global_load_dword v186, v3, s[6:7]
	v_add_u32_e32 v1, 0x4000, v1
	v_add_u32_e32 v2, 0x2000, v2
	v_add_u32_e32 v3, 4, v3
	s_waitcnt vmcnt(0)
	s_movk_i32 s10, 32
.Lscan_P_loop:
	s_waitcnt vmcnt(23)
	ds_read_b128 v[32:35], v8 offset:0
	ds_read_b128 v[36:39], v8 offset:4352
	ds_read_b128 v[40:43], v8 offset:64
	ds_read_b128 v[44:47], v8 offset:4416
	ds_read_b128 v[48:51], v8 offset:128
	ds_read_b128 v[52:55], v8 offset:4480
	ds_read_b128 v[56:59], v8 offset:192
	ds_read_b128 v[60:63], v8 offset:4544
	global_load_dwordx4 v[216:219], v1, s[0:1]
	global_load_dwordx4 v[220:223], v1, s[0:1] offset:1024
	s_waitcnt vmcnt(21)
	v_mul_f32_e32 v16, v184, v16
	v_mul_f32_e32 v17, v184, v17
	v_mul_f32_e32 v18, v184, v18
	v_mul_f32_e32 v19, v184, v19
	global_load_dwordx4 v[224:227], v1, s[0:1] offset:2048
	v_mul_f32_e32 v20, v184, v20
	v_mul_f32_e32 v21, v184, v21
	v_mul_f32_e32 v22, v184, v22
	v_mul_f32_e32 v23, v184, v23
	global_load_dwordx4 v[228:231], v1, s[0:1] offset:3072
	s_waitcnt lgkmcnt(6)
	v_mfma_f32_16x16x32_bf16 v[24:27], v[72:75], v[32:35], 0
	v_mfma_f32_16x16x32_bf16 v[28:31], v[72:75], v[36:39], 0
	global_load_dwordx4 v[232:235], v2, s[2:3]
	s_waitcnt lgkmcnt(4)
	v_mfma_f32_16x16x32_bf16 v[24:27], v[76:79], v[40:43], v[24:27]
	v_mfma_f32_16x16x32_bf16 v[28:31], v[76:79], v[44:47], v[28:31]
	global_load_dwordx4 v[240:243], v1, s[4:5]
	s_waitcnt lgkmcnt(2)
	v_mfma_f32_16x16x32_bf16 v[24:27], v[80:83], v[48:51], v[24:27]
	v_mfma_f32_16x16x32_bf16 v[28:31], v[80:83], v[52:55], v[28:31]
	global_load_dwordx4 v[244:247], v1, s[4:5] offset:1024
	s_waitcnt lgkmcnt(0)
	v_mfma_f32_16x16x32_bf16 v[24:27], v[84:87], v[56:59], v[24:27]
	v_mfma_f32_16x16x32_bf16 v[28:31], v[84:87], v[60:63], v[28:31]
	global_load_dword v187, v3, s[6:7]
	v_add_u32_e32 v1, 0x4000, v1
	v_add_u32_e32 v2, 0x2000, v2
	v_add_u32_e32 v3, 4, v3
	s_waitcnt lgkmcnt(0)
	s_barrier
	ds_read_b128 v[32:35], v9 offset:17408
	ds_read_b128 v[36:39], v9 offset:19712
	ds_read_b128 v[40:43], v9 offset:17472
	ds_read_b128 v[44:47], v9 offset:19776
	s_waitcnt lgkmcnt(2)
	v_mfma_f32_16x16x32_bf16 v[16:19], v[96:99], v[32:35], v[16:19]
	v_mfma_f32_16x16x32_bf16 v[20:23], v[96:99], v[36:39], v[20:23]
	v_mfma_f32_16x16x32_bf16 v[24:27], v[88:91], v[32:35], v[24:27]
	v_mfma_f32_16x16x32_bf16 v[28:31], v[88:91], v[36:39], v[28:31]
	s_waitcnt lgkmcnt(0)
	v_mfma_f32_16x16x32_bf16 v[16:19], v[100:103], v[40:43], v[16:19]
	v_mfma_f32_16x16x32_bf16 v[20:23], v[100:103], v[44:47], v[20:23]
	s_nop 7
	v_cvt_pk_bf16_f32 v64, v16, v17
	v_cvt_pk_bf16_f32 v65, v18, v19
	v_cvt_pk_bf16_f32 v66, v20, v21
	v_cvt_pk_bf16_f32 v67, v22, v23
	ds_write_b64 v11, v[64:65] offset:8704
	ds_write_b64 v11, v[66:67] offset:13056
	v_cvt_pk_bf16_f32 v68, v24, v25
	v_cvt_pk_bf16_f32 v69, v26, v27
	v_cvt_pk_bf16_f32 v70, v28, v29
	v_cvt_pk_bf16_f32 v71, v30, v31
	ds_write_b16 v13, v68 offset:0
	ds_write_b16_d16_hi v13, v68 offset:80
	ds_write_b16 v13, v69 offset:160
	ds_write_b16_d16_hi v13, v69 offset:240
	ds_write_b16 v13, v70 offset:32
	ds_write_b16_d16_hi v13, v70 offset:112
	ds_write_b16 v13, v71 offset:192
	ds_write_b16_d16_hi v13, v71 offset:272
	ds_read_b128 v[176:179], v172
	s_waitcnt lgkmcnt(0)
	s_barrier
	global_store_dwordx4 v12, v[176:179], s[8:9]
	v_add_u32_e32 v12, 0x20000, v12
	s_waitcnt vmcnt(23)
	ds_read_b128 v[32:35], v8 offset:8704
	ds_read_b128 v[36:39], v8 offset:13056
	ds_read_b128 v[40:43], v8 offset:8768
	ds_read_b128 v[44:47], v8 offset:13120
	ds_read_b128 v[48:51], v8 offset:8832
	ds_read_b128 v[52:55], v8 offset:13184
	ds_read_b128 v[56:59], v8 offset:8896
	ds_read_b128 v[60:63], v8 offset:13248
	global_load_dwordx4 v[72:75], v1, s[0:1]
	global_load_dwordx4 v[76:79], v1, s[0:1] offset:1024
	s_waitcnt vmcnt(21)
	v_mul_f32_e32 v16, v185, v16
	v_mul_f32_e32 v17, v185, v17
	v_mul_f32_e32 v18, v185, v18
	v_mul_f32_e32 v19, v185, v19
	global_load_dwordx4 v[80:83], v1, s[0:1] offset:2048
	v_mul_f32_e32 v20, v185, v20
	v_mul_f32_e32 v21, v185, v21
	v_mul_f32_e32 v22, v185, v22
	v_mul_f32_e32 v23, v185, v23
	global_load_dwordx4 v[84:87], v1, s[0:1] offset:3072
	s_waitcnt lgkmcnt(6)
	v_mfma_f32_16x16x32_bf16 v[24:27], v[104:107], v[32:35], 0
	v_mfma_f32_16x16x32_bf16 v[28:31], v[104:107], v[36:39], 0
	global_load_dwordx4 v[88:91], v2, s[2:3]
	s_waitcnt lgkmcnt(4)
	v_mfma_f32_16x16x32_bf16 v[24:27], v[108:111], v[40:43], v[24:27]
	v_mfma_f32_16x16x32_bf16 v[28:31], v[108:111], v[44:47], v[28:31]
	global_load_dwordx4 v[96:99], v1, s[4:5]
	s_waitcnt lgkmcnt(2)
	v_mfma_f32_16x16x32_bf16 v[24:27], v[112:115], v[48:51], v[24:27]
	v_mfma_f32_16x16x32_bf16 v[28:31], v[112:115], v[52:55], v[28:31]
	global_load_dwordx4 v[100:103], v1, s[4:5] offset:1024
	s_waitcnt lgkmcnt(0)
	v_mfma_f32_16x16x32_bf16 v[24:27], v[116:119], v[56:59], v[24:27]
	v_mfma_f32_16x16x32_bf16 v[28:31], v[116:119], v[60:63], v[28:31]
	global_load_dword v184, v3, s[6:7]
	v_add_u32_e32 v1, 0x4000, v1
	v_add_u32_e32 v2, 0x2000, v2
	v_add_u32_e32 v3, 4, v3
	s_waitcnt lgkmcnt(0)
	s_barrier
	ds_read_b128 v[32:35], v9 offset:17408
	ds_read_b128 v[36:39], v9 offset:19712
	ds_read_b128 v[40:43], v9 offset:17472
	ds_read_b128 v[44:47], v9 offset:19776
	s_waitcnt lgkmcnt(2)
	v_mfma_f32_16x16x32_bf16 v[16:19], v[128:131], v[32:35], v[16:19]
	v_mfma_f32_16x16x32_bf16 v[20:23], v[128:131], v[36:39], v[20:23]
	v_mfma_f32_16x16x32_bf16 v[24:27], v[120:123], v[32:35], v[24:27]
	v_mfma_f32_16x16x32_bf16 v[28:31], v[120:123], v[36:39], v[28:31]
	s_waitcnt lgkmcnt(0)
	v_mfma_f32_16x16x32_bf16 v[16:19], v[132:135], v[40:43], v[16:19]
	v_mfma_f32_16x16x32_bf16 v[20:23], v[132:135], v[44:47], v[20:23]
	s_nop 7
	v_cvt_pk_bf16_f32 v64, v16, v17
	v_cvt_pk_bf16_f32 v65, v18, v19
	v_cvt_pk_bf16_f32 v66, v20, v21
	v_cvt_pk_bf16_f32 v67, v22, v23
	ds_write_b64 v11, v[64:65] offset:0
	ds_write_b64 v11, v[66:67] offset:4352
	v_cvt_pk_bf16_f32 v68, v24, v25
	v_cvt_pk_bf16_f32 v69, v26, v27
	v_cvt_pk_bf16_f32 v70, v28, v29
	v_cvt_pk_bf16_f32 v71, v30, v31
	ds_write_b16 v13, v68 offset:0
	ds_write_b16_d16_hi v13, v68 offset:80
	ds_write_b16 v13, v69 offset:160
	ds_write_b16_d16_hi v13, v69 offset:240
	ds_write_b16 v13, v70 offset:32
	ds_write_b16_d16_hi v13, v70 offset:112
	ds_write_b16 v13, v71 offset:192
	ds_write_b16_d16_hi v13, v71 offset:272
	ds_read_b128 v[176:179], v172
	s_waitcnt lgkmcnt(0)
	s_barrier
	global_store_dwordx4 v12, v[176:179], s[8:9]
	v_add_u32_e32 v12, 0x20000, v12
	s_waitcnt vmcnt(23)
	ds_read_b128 v[32:35], v8 offset:0
	ds_read_b128 v[36:39], v8 offset:4352
	ds_read_b128 v[40:43], v8 offset:64
	ds_read_b128 v[44:47], v8 offset:4416
	ds_read_b128 v[48:51], v8 offset:128
	ds_read_b128 v[52:55], v8 offset:4480
	ds_read_b128 v[56:59], v8 offset:192
	ds_read_b128 v[60:63], v8 offset:4544
	global_load_dwordx4 v[104:107], v1, s[0:1]
	global_load_dwordx4 v[108:111], v1, s[0:1] offset:1024
	s_waitcnt vmcnt(21)
	v_mul_f32_e32 v16, v186, v16
	v_mul_f32_e32 v17, v186, v17
	v_mul_f32_e32 v18, v186, v18
	v_mul_f32_e32 v19, v186, v19
	global_load_dwordx4 v[112:115], v1, s[0:1] offset:2048
	v_mul_f32_e32 v20, v186, v20
	v_mul_f32_e32 v21, v186, v21
	v_mul_f32_e32 v22, v186, v22
	v_mul_f32_e32 v23, v186, v23
	global_load_dwordx4 v[116:119], v1, s[0:1] offset:3072
	s_waitcnt lgkmcnt(6)
	v_mfma_f32_16x16x32_bf16 v[24:27], v[136:139], v[32:35], 0
	v_mfma_f32_16x16x32_bf16 v[28:31], v[136:139], v[36:39], 0
	global_load_dwordx4 v[120:123], v2, s[2:3]
	s_waitcnt lgkmcnt(4)
	v_mfma_f32_16x16x32_bf16 v[24:27], v[140:143], v[40:43], v[24:27]
	v_mfma_f32_16x16x32_bf16 v[28:31], v[140:143], v[44:47], v[28:31]
	global_load_dwordx4 v[128:131], v1, s[4:5]
	s_waitcnt lgkmcnt(2)
	v_mfma_f32_16x16x32_bf16 v[24:27], v[144:147], v[48:51], v[24:27]
	v_mfma_f32_16x16x32_bf16 v[28:31], v[144:147], v[52:55], v[28:31]
	global_load_dwordx4 v[132:135], v1, s[4:5] offset:1024
	s_waitcnt lgkmcnt(0)
	v_mfma_f32_16x16x32_bf16 v[24:27], v[148:151], v[56:59], v[24:27]
	v_mfma_f32_16x16x32_bf16 v[28:31], v[148:151], v[60:63], v[28:31]
	global_load_dword v185, v3, s[6:7]
	v_add_u32_e32 v1, 0x4000, v1
	v_add_u32_e32 v2, 0x2000, v2
	v_add_u32_e32 v3, 4, v3
	s_waitcnt lgkmcnt(0)
	s_barrier
	ds_read_b128 v[32:35], v9 offset:17408
	ds_read_b128 v[36:39], v9 offset:19712
	ds_read_b128 v[40:43], v9 offset:17472
	ds_read_b128 v[44:47], v9 offset:19776
	s_waitcnt lgkmcnt(2)
	v_mfma_f32_16x16x32_bf16 v[16:19], v[196:199], v[32:35], v[16:19]
	v_mfma_f32_16x16x32_bf16 v[20:23], v[196:199], v[36:39], v[20:23]
	v_mfma_f32_16x16x32_bf16 v[24:27], v[188:191], v[32:35], v[24:27]
	v_mfma_f32_16x16x32_bf16 v[28:31], v[188:191], v[36:39], v[28:31]
	s_waitcnt lgkmcnt(0)
	v_mfma_f32_16x16x32_bf16 v[16:19], v[200:203], v[40:43], v[16:19]
	v_mfma_f32_16x16x32_bf16 v[20:23], v[200:203], v[44:47], v[20:23]
	s_nop 7
	v_cvt_pk_bf16_f32 v64, v16, v17
	v_cvt_pk_bf16_f32 v65, v18, v19
	v_cvt_pk_bf16_f32 v66, v20, v21
	v_cvt_pk_bf16_f32 v67, v22, v23
	ds_write_b64 v11, v[64:65] offset:8704
	ds_write_b64 v11, v[66:67] offset:13056
	v_cvt_pk_bf16_f32 v68, v24, v25
	v_cvt_pk_bf16_f32 v69, v26, v27
	v_cvt_pk_bf16_f32 v70, v28, v29
	v_cvt_pk_bf16_f32 v71, v30, v31
	ds_write_b16 v13, v68 offset:0
	ds_write_b16_d16_hi v13, v68 offset:80
	ds_write_b16 v13, v69 offset:160
	ds_write_b16_d16_hi v13, v69 offset:240
	ds_write_b16 v13, v70 offset:32
	ds_write_b16_d16_hi v13, v70 offset:112
	ds_write_b16 v13, v71 offset:192
	ds_write_b16_d16_hi v13, v71 offset:272
	ds_read_b128 v[176:179], v172
	s_waitcnt lgkmcnt(0)
	s_barrier
	global_store_dwordx4 v12, v[176:179], s[8:9]
	v_add_u32_e32 v12, 0x20000, v12
	s_waitcnt vmcnt(23)
	ds_read_b128 v[32:35], v8 offset:8704
	ds_read_b128 v[36:39], v8 offset:13056
	ds_read_b128 v[40:43], v8 offset:8768
	ds_read_b128 v[44:47], v8 offset:13120
	ds_read_b128 v[48:51], v8 offset:8832
	ds_read_b128 v[52:55], v8 offset:13184
	ds_read_b128 v[56:59], v8 offset:8896
	ds_read_b128 v[60:63], v8 offset:13248
	global_load_dwordx4 v[136:139], v1, s[0:1]
	global_load_dwordx4 v[140:143], v1, s[0:1] offset:1024
	s_waitcnt vmcnt(21)
	v_mul_f32_e32 v16, v187, v16
	v_mul_f32_e32 v17, v187, v17
	v_mul_f32_e32 v18, v187, v18
	v_mul_f32_e32 v19, v187, v19
	global_load_dwordx4 v[144:147], v1, s[0:1] offset:2048
	v_mul_f32_e32 v20, v187, v20
	v_mul_f32_e32 v21, v187, v21
	v_mul_f32_e32 v22, v187, v22
	v_mul_f32_e32 v23, v187, v23
	global_load_dwordx4 v[148:151], v1, s[0:1] offset:3072
	s_waitcnt lgkmcnt(6)
	v_mfma_f32_16x16x32_bf16 v[24:27], v[216:219], v[32:35], 0
	v_mfma_f32_16x16x32_bf16 v[28:31], v[216:219], v[36:39], 0
	global_load_dwordx4 v[188:191], v2, s[2:3]
	s_waitcnt lgkmcnt(4)
	v_mfma_f32_16x16x32_bf16 v[24:27], v[220:223], v[40:43], v[24:27]
	v_mfma_f32_16x16x32_bf16 v[28:31], v[220:223], v[44:47], v[28:31]
	global_load_dwordx4 v[196:199], v1, s[4:5]
	s_waitcnt lgkmcnt(2)
	v_mfma_f32_16x16x32_bf16 v[24:27], v[224:227], v[48:51], v[24:27]
	v_mfma_f32_16x16x32_bf16 v[28:31], v[224:227], v[52:55], v[28:31]
	global_load_dwordx4 v[200:203], v1, s[4:5] offset:1024
	s_waitcnt lgkmcnt(0)
	v_mfma_f32_16x16x32_bf16 v[24:27], v[228:231], v[56:59], v[24:27]
	v_mfma_f32_16x16x32_bf16 v[28:31], v[228:231], v[60:63], v[28:31]
	global_load_dword v186, v3, s[6:7]
	v_add_u32_e32 v1, 0x4000, v1
	v_add_u32_e32 v2, 0x2000, v2
	v_add_u32_e32 v3, 4, v3
	s_waitcnt lgkmcnt(0)
	s_barrier
	ds_read_b128 v[32:35], v9 offset:17408
	ds_read_b128 v[36:39], v9 offset:19712
	ds_read_b128 v[40:43], v9 offset:17472
	ds_read_b128 v[44:47], v9 offset:19776
	s_waitcnt lgkmcnt(2)
	v_mfma_f32_16x16x32_bf16 v[16:19], v[240:243], v[32:35], v[16:19]
	v_mfma_f32_16x16x32_bf16 v[20:23], v[240:243], v[36:39], v[20:23]
	v_mfma_f32_16x16x32_bf16 v[24:27], v[232:235], v[32:35], v[24:27]
	v_mfma_f32_16x16x32_bf16 v[28:31], v[232:235], v[36:39], v[28:31]
	s_waitcnt lgkmcnt(0)
	v_mfma_f32_16x16x32_bf16 v[16:19], v[244:247], v[40:43], v[16:19]
	v_mfma_f32_16x16x32_bf16 v[20:23], v[244:247], v[44:47], v[20:23]
	s_nop 7
	v_cvt_pk_bf16_f32 v64, v16, v17
	v_cvt_pk_bf16_f32 v65, v18, v19
	v_cvt_pk_bf16_f32 v66, v20, v21
	v_cvt_pk_bf16_f32 v67, v22, v23
	ds_write_b64 v11, v[64:65] offset:0
	ds_write_b64 v11, v[66:67] offset:4352
	v_cvt_pk_bf16_f32 v68, v24, v25
	v_cvt_pk_bf16_f32 v69, v26, v27
	v_cvt_pk_bf16_f32 v70, v28, v29
	v_cvt_pk_bf16_f32 v71, v30, v31
	ds_write_b16 v13, v68 offset:0
	ds_write_b16_d16_hi v13, v68 offset:80
	ds_write_b16 v13, v69 offset:160
	ds_write_b16_d16_hi v13, v69 offset:240
	ds_write_b16 v13, v70 offset:32
	ds_write_b16_d16_hi v13, v70 offset:112
	ds_write_b16 v13, v71 offset:192
	ds_write_b16_d16_hi v13, v71 offset:272
	ds_read_b128 v[176:179], v172
	s_waitcnt lgkmcnt(0)
	s_barrier
	global_store_dwordx4 v12, v[176:179], s[8:9]
	v_add_u32_e32 v12, 0x20000, v12
	s_sub_u32 s10, s10, 1
	s_cmp_lg_u32 s10, 0
	s_cbranch_scc1 .Lscan_P_loop
